# GEMM tile start: 128 accumulator registers zeroed with 64 v_mov_b64 instead of 128 v_mov_b32
# speedup vs baseline: 1.0054x; 1.0001x over previous
; __device__ __forceinline__ void gemm_phase(LAS unsigned char* lds, const Gemm g, const StaticOrder& S, const Epi& E) {
;     ...
; #pragma unroll
;         for (int a = 0; a < 2; ++a)
; #pragma unroll
;             for (int b = 0; b < 2; ++b)
; #pragma unroll
;                 for (int m = 0; m < 4; ++m)
; #pragma unroll
;                     for (int n = 0; n < 2; ++n) acc[a][b][m][n] = (f32x4){0.f, 0.f, 0.f, 0.f};
;         cur = nxt; cA = nA; cB = nB; ++ui;
.LBB0_761:
	s_add_u32 s0, s34, 0x80
	s_addc_u32 s1, s35, 0
	s_add_u32 s27, s36, 0x100
	s_addc_u32 s33, s37, 0
	s_mov_b32 s34, 0
	v_mov_b64_e32 v[0:1], 0
	v_mov_b64_e32 v[2:3], 0
	v_mov_b64_e32 v[4:5], 0
	v_mov_b64_e32 v[6:7], 0
	v_mov_b64_e32 v[8:9], 0
	v_mov_b64_e32 v[10:11], 0
	v_mov_b64_e32 v[12:13], 0
	v_mov_b64_e32 v[14:15], 0
	v_mov_b64_e32 v[16:17], 0
	v_mov_b64_e32 v[18:19], 0
	v_mov_b64_e32 v[20:21], 0
	v_mov_b64_e32 v[22:23], 0
	v_mov_b64_e32 v[24:25], 0
	v_mov_b64_e32 v[26:27], 0
	v_mov_b64_e32 v[28:29], 0
	v_mov_b64_e32 v[30:31], 0
	v_mov_b64_e32 v[32:33], 0
	v_mov_b64_e32 v[34:35], 0
	v_mov_b64_e32 v[36:37], 0
	v_mov_b64_e32 v[38:39], 0
	v_mov_b64_e32 v[40:41], 0
	v_mov_b64_e32 v[42:43], 0
	v_mov_b64_e32 v[44:45], 0
	v_mov_b64_e32 v[46:47], 0
	v_mov_b64_e32 v[48:49], 0
	v_mov_b64_e32 v[50:51], 0
	v_mov_b64_e32 v[52:53], 0
	v_mov_b64_e32 v[54:55], 0
	v_mov_b64_e32 v[56:57], 0
	v_mov_b64_e32 v[58:59], 0
	v_mov_b64_e32 v[60:61], 0
	v_mov_b64_e32 v[62:63], 0
	v_mov_b64_e32 v[64:65], 0
	v_mov_b64_e32 v[66:67], 0
	v_mov_b64_e32 v[68:69], 0
	v_mov_b64_e32 v[70:71], 0
	v_mov_b64_e32 v[72:73], 0
	v_mov_b64_e32 v[74:75], 0
	v_mov_b64_e32 v[76:77], 0
	v_mov_b64_e32 v[78:79], 0
	v_mov_b64_e32 v[80:81], 0
	v_mov_b64_e32 v[82:83], 0
	v_mov_b64_e32 v[84:85], 0
	v_mov_b64_e32 v[86:87], 0
	v_mov_b64_e32 v[88:89], 0
	v_mov_b64_e32 v[90:91], 0
	v_mov_b64_e32 v[92:93], 0
	v_mov_b64_e32 v[94:95], 0
	v_mov_b64_e32 v[96:97], 0
	v_mov_b64_e32 v[98:99], 0
	v_mov_b64_e32 v[100:101], 0
	v_mov_b64_e32 v[102:103], 0
	v_mov_b64_e32 v[104:105], 0
	v_mov_b64_e32 v[106:107], 0
	v_mov_b64_e32 v[108:109], 0
	v_mov_b64_e32 v[110:111], 0
	v_mov_b64_e32 v[112:113], 0
	v_mov_b64_e32 v[114:115], 0
	v_mov_b64_e32 v[116:117], 0
	v_mov_b64_e32 v[118:119], 0
	v_mov_b64_e32 v[120:121], 0
	v_mov_b64_e32 v[122:123], 0
	v_mov_b64_e32 v[124:125], 0
	v_mov_b64_e32 v[126:127], 0
	v_add_u32_e32 v224, 0x10000, v238
	v_add_u32_e32 v225, 0x14000, v238
	v_add_u32_e32 v241, 0x18000, v238
	v_add_u32_e32 v248, 0x1c000, v238
	s_cmpk_gt_u32 s57, 0xff
	s_cbranch_scc1 .Lprio_skip
	s_setprio 1
